# grid-barrier seams 2-9: the XCD leader issues a first buffer_wbl2 right after its own arrival (while the XCD's other workgroups are still arriving), so the writeback behind the last arrival finds litt
# baseline (speedup 1.0000x reference)
; __device__ __forceinline__ int lane_id_asm() { int l; asm volatile("v_mbcnt_lo_u32_b32 %0, -1, 0\n\tv_mbcnt_hi_u32_b32 %0, -1, %0" : "=v"(l)); return l; }
; __device__ __forceinline__ unsigned xb_ld(unsigned* p)              { return __hip_atomic_load(p, __ATOMIC_RELAXED, __HIP_MEMORY_SCOPE_AGENT); }
; __device__ __forceinline__ unsigned xb_add(unsigned* p, unsigned v) { return __hip_atomic_fetch_add(p, v, __ATOMIC_RELAXED, __HIP_MEMORY_SCOPE_AGENT); }
; #define XB_SPIN(cond, bar) do { unsigned _sp = 0; while (cond) { __builtin_amdgcn_s_sleep(1); \
;     if ((++_sp & 255u) == 0u) { if (xb_ld(&(bar)[XB_TMO])) break; if (_sp > XB_SPIN_CAP) { atomicAdd(&(bar)[XB_TMO], 1u); break; } } } } while (0)
; __device__ __forceinline__ void xcd_barrier(const XcdBarrier& b, const int wid) {
;     asm volatile("s_waitcnt vmcnt(0)" ::: "memory");
;     __syncthreads();
;     if (wid == 0 && lane_id_asm() == 0) {
;         unsigned* bar = b.bar;
;         __builtin_amdgcn_s_waitcnt(0);
;         unsigned nloc = b.st[0], nx = b.st[1];
;         if (nloc == 0u) { xcd_barrier_complete(bar, b.x, nloc, nx); b.st[0] = nloc; b.st[1] = nx; }
;         const unsigned old = xb_add(&bar[XB_XSUB(b.x)], 1u);
;         const unsigned gen = old / nloc;
;         if (old + 1u == (gen + 1u) * nloc) {
;             __builtin_amdgcn_fence(__ATOMIC_RELEASE, "agent");
;             asm volatile("s_waitcnt vmcnt(0)" ::: "memory");
;             const unsigned og = xb_add(&bar[XB_TOP], 1u);
;             const unsigned tg = og / nx;
;             if (og + 1u == (tg + 1u) * nx) xb_add(&bar[XB_TOPGEN], 1u);
;             else XB_SPIN(xb_ld(&bar[XB_TOPGEN]) == tg, bar);
.LBB0_686:
	v_readlane_b32 s0, v254, 13
	v_readlane_b32 s1, v254, 14
	s_and_b64 vcc, exec, s[0:1]
	s_cbranch_vccnz .LBB0_738
	s_waitcnt vmcnt(0)
	s_cmp_gt_u32 s79, 63
	s_waitcnt vmcnt(0) lgkmcnt(0)
	s_barrier
	s_cbranch_scc1 .LBB0_737
	v_mbcnt_lo_u32_b32 v0, -1, 0
	v_mbcnt_hi_u32_b32 v0, -1, v0
	s_nop 0
	v_cmp_eq_u32_e32 vcc, 0, v0
	s_and_saveexec_b64 s[0:1], vcc
	s_cbranch_execz .LBB0_736
	v_readlane_b32 s2, v254, 9
	s_waitcnt vmcnt(0) expcnt(0) lgkmcnt(0)
	s_nop 0
	v_mov_b32_e32 v0, s2
	ds_read_b32 v2, v0
	ds_read_b32 v3, v0 offset:4
	ds_read_b32 v4, v0 offset:8
	ds_read_b32 v5, v0 offset:12
	v_readlane_b32 s2, v254, 8
	s_lshl_b32 s2, s2, 8
	v_readlane_b32 s4, v254, 6
	v_readlane_b32 s5, v254, 7
	s_add_u32 s2, s4, s2
	s_addc_u32 s3, s5, 0
	v_mov_b32_e32 v1, 0x1000
	v_mov_b32_e32 v6, 1
	global_atomic_add v1, v6, s[2:3] offset:1024
	buffer_inv sc1
	s_waitcnt lgkmcnt(0)
	v_add_u32_e32 v6, 1, v4
	ds_write_b32 v0, v6 offset:8
	v_add_u32_e32 v4, 2, v4
	v_mul_lo_u32 v2, v2, v4
	v_mul_lo_u32 v3, v3, v4
	s_add_u32 s10, s86, 0x7400
	s_addc_u32 s11, s87, 0
	s_mov_b32 s4, 0x200000
	v_cmp_eq_u32_e32 vcc, 0, v5
	s_cbranch_vccnz .Lxb2_wait
	buffer_wbl2 sc1

; __device__ __forceinline__ int lane_id_asm() { int l; asm volatile("v_mbcnt_lo_u32_b32 %0, -1, 0\n\tv_mbcnt_hi_u32_b32 %0, -1, %0" : "=v"(l)); return l; }
; __device__ __forceinline__ unsigned xb_ld(unsigned* p)              { return __hip_atomic_load(p, __ATOMIC_RELAXED, __HIP_MEMORY_SCOPE_AGENT); }
; __device__ __forceinline__ unsigned xb_add(unsigned* p, unsigned v) { return __hip_atomic_fetch_add(p, v, __ATOMIC_RELAXED, __HIP_MEMORY_SCOPE_AGENT); }
; #define XB_SPIN(cond, bar) do { unsigned _sp = 0; while (cond) { __builtin_amdgcn_s_sleep(1); \
;     if ((++_sp & 255u) == 0u) { if (xb_ld(&(bar)[XB_TMO])) break; if (_sp > XB_SPIN_CAP) { atomicAdd(&(bar)[XB_TMO], 1u); break; } } } } while (0)
; __device__ __forceinline__ void xcd_barrier(const XcdBarrier& b, const int wid) {
;     asm volatile("s_waitcnt vmcnt(0)" ::: "memory");
;     __syncthreads();
;     if (wid == 0 && lane_id_asm() == 0) {
;         unsigned* bar = b.bar;
;         __builtin_amdgcn_s_waitcnt(0);
;         unsigned nloc = b.st[0], nx = b.st[1];
;         if (nloc == 0u) { xcd_barrier_complete(bar, b.x, nloc, nx); b.st[0] = nloc; b.st[1] = nx; }
;         const unsigned old = xb_add(&bar[XB_XSUB(b.x)], 1u);
;         const unsigned gen = old / nloc;
;         if (old + 1u == (gen + 1u) * nloc) {
;             __builtin_amdgcn_fence(__ATOMIC_RELEASE, "agent");
;             asm volatile("s_waitcnt vmcnt(0)" ::: "memory");
;             const unsigned og = xb_add(&bar[XB_TOP], 1u);
;             const unsigned tg = og / nx;
;             if (og + 1u == (tg + 1u) * nx) xb_add(&bar[XB_TOPGEN], 1u);
;             else XB_SPIN(xb_ld(&bar[XB_TOPGEN]) == tg, bar);
.LBB0_820:
	v_readlane_b32 s0, v254, 13
	v_readlane_b32 s1, v254, 14
	s_and_b64 vcc, exec, s[0:1]
	s_cbranch_vccnz .LBB0_872
	s_waitcnt vmcnt(0)
	s_cmp_gt_u32 s79, 63
	s_waitcnt vmcnt(0)
	s_barrier
	s_cbranch_scc1 .LBB0_871
	v_mbcnt_lo_u32_b32 v0, -1, 0
	v_mbcnt_hi_u32_b32 v0, -1, v0
	s_nop 0
	v_cmp_eq_u32_e32 vcc, 0, v0
	s_and_saveexec_b64 s[0:1], vcc
	s_cbranch_execz .LBB0_870
	v_readlane_b32 s2, v254, 9
	s_waitcnt vmcnt(0) expcnt(0) lgkmcnt(0)
	s_nop 0
	v_mov_b32_e32 v0, s2
	ds_read_b32 v2, v0
	ds_read_b32 v3, v0 offset:4
	ds_read_b32 v4, v0 offset:8
	ds_read_b32 v5, v0 offset:12
	v_readlane_b32 s2, v254, 8
	s_lshl_b32 s2, s2, 8
	v_readlane_b32 s4, v254, 6
	v_readlane_b32 s5, v254, 7
	s_add_u32 s2, s4, s2
	s_addc_u32 s3, s5, 0
	v_mov_b32_e32 v1, 0x1000
	v_mov_b32_e32 v6, 1
	global_atomic_add v1, v6, s[2:3] offset:1024
	buffer_inv sc1
	s_waitcnt lgkmcnt(0)
	v_add_u32_e32 v6, 1, v4
	ds_write_b32 v0, v6 offset:8
	v_add_u32_e32 v4, 2, v4
	v_mul_lo_u32 v2, v2, v4
	v_mul_lo_u32 v3, v3, v4
	s_add_u32 s10, s86, 0x7400
	s_addc_u32 s11, s87, 0
	s_mov_b32 s4, 0x200000
	v_cmp_eq_u32_e32 vcc, 0, v5
	s_cbranch_vccnz .Lxb3_wait
	buffer_wbl2 sc1

; __device__ __forceinline__ int lane_id_asm() { int l; asm volatile("v_mbcnt_lo_u32_b32 %0, -1, 0\n\tv_mbcnt_hi_u32_b32 %0, -1, %0" : "=v"(l)); return l; }
; __device__ __forceinline__ unsigned xb_ld(unsigned* p)              { return __hip_atomic_load(p, __ATOMIC_RELAXED, __HIP_MEMORY_SCOPE_AGENT); }
; __device__ __forceinline__ unsigned xb_add(unsigned* p, unsigned v) { return __hip_atomic_fetch_add(p, v, __ATOMIC_RELAXED, __HIP_MEMORY_SCOPE_AGENT); }
; #define XB_SPIN(cond, bar) do { unsigned _sp = 0; while (cond) { __builtin_amdgcn_s_sleep(1); \
;     if ((++_sp & 255u) == 0u) { if (xb_ld(&(bar)[XB_TMO])) break; if (_sp > XB_SPIN_CAP) { atomicAdd(&(bar)[XB_TMO], 1u); break; } } } } while (0)
; __device__ __forceinline__ void xcd_barrier(const XcdBarrier& b, const int wid) {
;     asm volatile("s_waitcnt vmcnt(0)" ::: "memory");
;     __syncthreads();
;     if (wid == 0 && lane_id_asm() == 0) {
;         unsigned* bar = b.bar;
;         __builtin_amdgcn_s_waitcnt(0);
;         unsigned nloc = b.st[0], nx = b.st[1];
;         if (nloc == 0u) { xcd_barrier_complete(bar, b.x, nloc, nx); b.st[0] = nloc; b.st[1] = nx; }
;         const unsigned old = xb_add(&bar[XB_XSUB(b.x)], 1u);
;         const unsigned gen = old / nloc;
;         if (old + 1u == (gen + 1u) * nloc) {
;             __builtin_amdgcn_fence(__ATOMIC_RELEASE, "agent");
;             asm volatile("s_waitcnt vmcnt(0)" ::: "memory");
;             const unsigned og = xb_add(&bar[XB_TOP], 1u);
;             const unsigned tg = og / nx;
;             if (og + 1u == (tg + 1u) * nx) xb_add(&bar[XB_TOPGEN], 1u);
;             else XB_SPIN(xb_ld(&bar[XB_TOPGEN]) == tg, bar);
.LBB0_1476:
	s_and_b64 vcc, exec, s[60:61]
	s_cbranch_vccnz .LBB0_1528
	s_waitcnt vmcnt(0)
	s_cmp_gt_u32 s79, 63
	s_waitcnt vmcnt(0) lgkmcnt(0)
	s_barrier
	s_cbranch_scc1 .LBB0_1527
	v_mbcnt_lo_u32_b32 v0, -1, 0
	v_mbcnt_hi_u32_b32 v0, -1, v0
	s_nop 0
	v_cmp_eq_u32_e32 vcc, 0, v0
	s_and_saveexec_b64 s[0:1], vcc
	s_cbranch_execz .LBB0_1526
	v_readlane_b32 s2, v254, 9
	s_waitcnt vmcnt(0) expcnt(0) lgkmcnt(0)
	s_nop 0
	v_mov_b32_e32 v0, s2
	ds_read_b32 v2, v0
	ds_read_b32 v3, v0 offset:4
	ds_read_b32 v4, v0 offset:8
	ds_read_b32 v5, v0 offset:12
	v_readlane_b32 s2, v254, 8
	s_lshl_b32 s2, s2, 8
	v_readlane_b32 s4, v254, 6
	v_readlane_b32 s5, v254, 7
	s_add_u32 s2, s4, s2
	s_addc_u32 s3, s5, 0
	v_mov_b32_e32 v1, 0x1000
	v_mov_b32_e32 v6, 1
	global_atomic_add v1, v6, s[2:3] offset:1024
	buffer_inv sc1
	s_waitcnt lgkmcnt(0)
	v_add_u32_e32 v6, 1, v4
	ds_write_b32 v0, v6 offset:8
	v_add_u32_e32 v4, 2, v4
	v_mul_lo_u32 v2, v2, v4
	v_mul_lo_u32 v3, v3, v4
	s_add_u32 s10, s86, 0x7400
	s_addc_u32 s11, s87, 0
	s_mov_b32 s4, 0x200000
	v_cmp_eq_u32_e32 vcc, 0, v5
	s_cbranch_vccnz .Lxb5_wait
	buffer_wbl2 sc1

; __device__ __forceinline__ int lane_id_asm() { int l; asm volatile("v_mbcnt_lo_u32_b32 %0, -1, 0\n\tv_mbcnt_hi_u32_b32 %0, -1, %0" : "=v"(l)); return l; }
; __device__ __forceinline__ unsigned xb_ld(unsigned* p)              { return __hip_atomic_load(p, __ATOMIC_RELAXED, __HIP_MEMORY_SCOPE_AGENT); }
; __device__ __forceinline__ unsigned xb_add(unsigned* p, unsigned v) { return __hip_atomic_fetch_add(p, v, __ATOMIC_RELAXED, __HIP_MEMORY_SCOPE_AGENT); }
; #define XB_SPIN(cond, bar) do { unsigned _sp = 0; while (cond) { __builtin_amdgcn_s_sleep(1); \
;     if ((++_sp & 255u) == 0u) { if (xb_ld(&(bar)[XB_TMO])) break; if (_sp > XB_SPIN_CAP) { atomicAdd(&(bar)[XB_TMO], 1u); break; } } } } while (0)
; __device__ __forceinline__ void xcd_barrier(const XcdBarrier& b, const int wid) {
;     asm volatile("s_waitcnt vmcnt(0)" ::: "memory");
;     __syncthreads();
;     if (wid == 0 && lane_id_asm() == 0) {
;         unsigned* bar = b.bar;
;         __builtin_amdgcn_s_waitcnt(0);
;         unsigned nloc = b.st[0], nx = b.st[1];
;         if (nloc == 0u) { xcd_barrier_complete(bar, b.x, nloc, nx); b.st[0] = nloc; b.st[1] = nx; }
;         const unsigned old = xb_add(&bar[XB_XSUB(b.x)], 1u);
;         const unsigned gen = old / nloc;
;         if (old + 1u == (gen + 1u) * nloc) {
;             __builtin_amdgcn_fence(__ATOMIC_RELEASE, "agent");
;             asm volatile("s_waitcnt vmcnt(0)" ::: "memory");
;             const unsigned og = xb_add(&bar[XB_TOP], 1u);
;             const unsigned tg = og / nx;
;             if (og + 1u == (tg + 1u) * nx) xb_add(&bar[XB_TOPGEN], 1u);
;             else XB_SPIN(xb_ld(&bar[XB_TOPGEN]) == tg, bar);
.LBB0_1621:
	s_and_b64 vcc, exec, s[60:61]
	s_cbranch_vccnz .LBB0_1673
	s_waitcnt vmcnt(0)
	s_cmp_gt_u32 s79, 63
	s_waitcnt vmcnt(0)
	s_barrier
	s_cbranch_scc1 .LBB0_1672
	v_mbcnt_lo_u32_b32 v0, -1, 0
	v_mbcnt_hi_u32_b32 v0, -1, v0
	s_nop 0
	v_cmp_eq_u32_e32 vcc, 0, v0
	s_and_saveexec_b64 s[0:1], vcc
	s_cbranch_execz .LBB0_1671
	v_readlane_b32 s2, v254, 9
	s_waitcnt vmcnt(0) expcnt(0) lgkmcnt(0)
	s_nop 0
	v_mov_b32_e32 v0, s2
	ds_read_b32 v2, v0
	ds_read_b32 v3, v0 offset:4
	ds_read_b32 v4, v0 offset:8
	ds_read_b32 v5, v0 offset:12
	v_readlane_b32 s2, v254, 8
	s_lshl_b32 s2, s2, 8
	v_readlane_b32 s4, v254, 6
	v_readlane_b32 s5, v254, 7
	s_add_u32 s2, s4, s2
	s_addc_u32 s3, s5, 0
	v_mov_b32_e32 v1, 0x1000
	v_mov_b32_e32 v6, 1
	global_atomic_add v1, v6, s[2:3] offset:1024
	buffer_inv sc1
	s_waitcnt lgkmcnt(0)
	v_add_u32_e32 v6, 1, v4
	ds_write_b32 v0, v6 offset:8
	v_add_u32_e32 v4, 2, v4
	v_mul_lo_u32 v2, v2, v4
	v_mul_lo_u32 v3, v3, v4
	s_add_u32 s10, s86, 0x7400
	s_addc_u32 s11, s87, 0
	s_mov_b32 s4, 0x200000
	v_cmp_eq_u32_e32 vcc, 0, v5
	s_cbranch_vccnz .Lxb6_wait
	buffer_wbl2 sc1
